# QK gather prefetch depth 2 -> 5 tiles on top of the per-query bias bucket precompute
# speedup vs baseline: 1.0201x; 1.0036x over previous
; #define LAS __attribute__((address_space(3)))
; __device__ __forceinline__ void dsa_unit(int wv, const Args& A, LAS unsigned char* lds, int s, int qt) {
;     ...
;         const int qq = 2 * w + qi2; int n = __builtin_amdgcn_readfirstlane((int)cnt[qq]); n = n > 256 ? 256 : n;
;         const size_t qrow = qrow0 + qq; const int qpos = qpos0 + qq;
;         LAS const unsigned short* lst = ci + qq * CAP;
;         long qf[8];
; #pragma unroll
;         for (int kk = 0; kk < 8; ++kk) { qf[kk] = 0;
;             if (fr < 8 && (fr >> 2) == (kk >> 2)) { const h16x8 q = __builtin_bit_cast(h16x8, *(const u32x4*)(PROJ + qrow * PW + C_Q + fr * 128 + ((kk >> 1) & 1) * 64 + fq * 16 + (kk & 1) * 8));
;                 f32x4 a, bq;
; #pragma unroll
;                 for (int e = 0; e < 4; ++e) { a[e] = 16.f * (float)q[e]; bq[e] = 16.f * (float)q[4 + e]; }
;                 qf[kk] = __builtin_bit_cast(long, pack_fp8x8(a, bq)); } }
;         const int nt = n >> 4;
.LBB0_1429:
	s_or_b32 s1, s0, s94
	s_lshl_b32 s12, s1, 2
	s_add_i32 s12, s12, 0
	s_add_i32 s12, s12, 0x1c800
	v_mov_b32_e32 v0, s12
	ds_read_b32 v0, v0
	s_ashr_i32 s12, s1, 31
	s_add_u32 s22, s1, s5
	s_addc_u32 s23, s12, 0
	s_mul_i32 s14, s23, 0x2e00
	v_mad_u64_u32 v[2:3], s[12:13], s22, v157, v[22:23]
	s_waitcnt lgkmcnt(0)
	v_readfirstlane_b32 s30, v0
	v_add_u32_e32 v3, s14, v3
	v_mov_b64_e32 v[32:33], 0
	v_mov_b64_e32 v[34:35], 0
	v_mov_b64_e32 v[36:37], 0
	v_mov_b64_e32 v[38:39], 0
	v_mov_b64_e32 v[40:41], 0
	v_mov_b64_e32 v[42:43], 0
	v_mov_b64_e32 v[44:45], 0
	v_mov_b64_e32 v[46:47], 0
	s_or_b64 s[14:15], s[10:11], s[20:21]
	s_and_saveexec_b64 s[12:13], s[14:15]
	global_load_dwordx4 v[56:59], v[2:3], off
	global_load_dwordx4 v[60:63], v[2:3], off offset:16
	global_load_dwordx4 v[64:67], v[2:3], off offset:128
	global_load_dwordx4 v[68:71], v[2:3], off offset:144
	s_waitcnt vmcnt(3)
	v_cvt_f32_f16_e32 v145, v56
	v_cvt_f32_f16_e32 v146, v58
	v_cvt_f32_f16_sdwa v147, v56 dst_sel:DWORD dst_unused:UNUSED_PAD src0_sel:WORD_1
	v_cvt_f32_f16_sdwa v148, v58 dst_sel:DWORD dst_unused:UNUSED_PAD src0_sel:WORD_1
	v_mul_f32_e32 v145, 0x41800000, v145
	v_mul_f32_e32 v146, 0x41800000, v146
	v_mul_f32_e32 v147, 0x41800000, v147
	v_mul_f32_e32 v148, 0x41800000, v148
	v_cvt_f32_f16_e32 v149, v57
	v_cvt_f32_f16_e32 v158, v59
	v_cvt_f32_f16_sdwa v159, v57 dst_sel:DWORD dst_unused:UNUSED_PAD src0_sel:WORD_1
	v_cvt_f32_f16_sdwa v160, v59 dst_sel:DWORD dst_unused:UNUSED_PAD src0_sel:WORD_1
	v_cvt_pk_fp8_f32 v72, v145, v147
	v_cvt_pk_fp8_f32 v73, v146, v148
	v_mul_f32_e32 v149, 0x41800000, v149
	v_mul_f32_e32 v158, 0x41800000, v158
	v_mul_f32_e32 v159, 0x41800000, v159
	v_mul_f32_e32 v160, 0x41800000, v160
	v_cvt_pk_fp8_f32 v72, v149, v159 op_sel:[0,0,1]
	v_cvt_pk_fp8_f32 v73, v158, v160 op_sel:[0,0,1]
	s_waitcnt vmcnt(2)
	v_cvt_f32_f16_e32 v145, v60
	v_cvt_f32_f16_e32 v146, v62
	v_cvt_f32_f16_sdwa v147, v60 dst_sel:DWORD dst_unused:UNUSED_PAD src0_sel:WORD_1
	v_cvt_f32_f16_sdwa v148, v62 dst_sel:DWORD dst_unused:UNUSED_PAD src0_sel:WORD_1
	v_mul_f32_e32 v145, 0x41800000, v145
	v_mul_f32_e32 v146, 0x41800000, v146
	v_mul_f32_e32 v147, 0x41800000, v147
	v_mul_f32_e32 v148, 0x41800000, v148
	v_cvt_f32_f16_e32 v149, v61
	v_cvt_f32_f16_e32 v158, v63
	v_cvt_f32_f16_sdwa v159, v61 dst_sel:DWORD dst_unused:UNUSED_PAD src0_sel:WORD_1
	v_cvt_f32_f16_sdwa v160, v63 dst_sel:DWORD dst_unused:UNUSED_PAD src0_sel:WORD_1
	v_cvt_pk_fp8_f32 v74, v145, v147
	v_cvt_pk_fp8_f32 v75, v146, v148
	v_mul_f32_e32 v149, 0x41800000, v149
	v_mul_f32_e32 v158, 0x41800000, v158
	v_mul_f32_e32 v159, 0x41800000, v159
	v_mul_f32_e32 v160, 0x41800000, v160
	v_cvt_pk_fp8_f32 v74, v149, v159 op_sel:[0,0,1]
	v_cvt_pk_fp8_f32 v75, v158, v160 op_sel:[0,0,1]
	s_waitcnt vmcnt(1)
	v_cvt_f32_f16_e32 v145, v64
	v_cvt_f32_f16_e32 v146, v66
	v_cvt_f32_f16_sdwa v147, v64 dst_sel:DWORD dst_unused:UNUSED_PAD src0_sel:WORD_1
	v_cvt_f32_f16_sdwa v148, v66 dst_sel:DWORD dst_unused:UNUSED_PAD src0_sel:WORD_1
	v_mul_f32_e32 v145, 0x41800000, v145
	v_mul_f32_e32 v146, 0x41800000, v146
	v_mul_f32_e32 v147, 0x41800000, v147
	v_mul_f32_e32 v148, 0x41800000, v148
	v_cvt_f32_f16_e32 v149, v65
	v_cvt_f32_f16_e32 v158, v67
	v_cvt_f32_f16_sdwa v159, v65 dst_sel:DWORD dst_unused:UNUSED_PAD src0_sel:WORD_1
	v_cvt_f32_f16_sdwa v160, v67 dst_sel:DWORD dst_unused:UNUSED_PAD src0_sel:WORD_1
	v_cvt_pk_fp8_f32 v76, v145, v147
	v_cvt_pk_fp8_f32 v77, v146, v148
	v_mul_f32_e32 v149, 0x41800000, v149
	v_mul_f32_e32 v158, 0x41800000, v158
	v_mul_f32_e32 v159, 0x41800000, v159
	v_mul_f32_e32 v160, 0x41800000, v160
	v_cvt_pk_fp8_f32 v76, v149, v159 op_sel:[0,0,1]
	v_cvt_pk_fp8_f32 v77, v158, v160 op_sel:[0,0,1]
	s_waitcnt vmcnt(0)
	v_cvt_f32_f16_e32 v145, v68
	v_cvt_f32_f16_e32 v146, v70
	v_cvt_f32_f16_sdwa v147, v68 dst_sel:DWORD dst_unused:UNUSED_PAD src0_sel:WORD_1
	v_cvt_f32_f16_sdwa v148, v70 dst_sel:DWORD dst_unused:UNUSED_PAD src0_sel:WORD_1
	v_mul_f32_e32 v145, 0x41800000, v145
	v_mul_f32_e32 v146, 0x41800000, v146
	v_mul_f32_e32 v147, 0x41800000, v147
	v_mul_f32_e32 v148, 0x41800000, v148
	v_cvt_f32_f16_e32 v149, v69
	v_cvt_f32_f16_e32 v158, v71
	v_cvt_f32_f16_sdwa v159, v69 dst_sel:DWORD dst_unused:UNUSED_PAD src0_sel:WORD_1
	v_cvt_f32_f16_sdwa v160, v71 dst_sel:DWORD dst_unused:UNUSED_PAD src0_sel:WORD_1
	v_cvt_pk_fp8_f32 v78, v145, v147
	v_cvt_pk_fp8_f32 v79, v146, v148
	v_mul_f32_e32 v149, 0x41800000, v149
	v_mul_f32_e32 v158, 0x41800000, v158
	v_mul_f32_e32 v159, 0x41800000, v159
	v_mul_f32_e32 v160, 0x41800000, v160
	v_cvt_pk_fp8_f32 v78, v149, v159 op_sel:[0,0,1]
	v_cvt_pk_fp8_f32 v79, v158, v160 op_sel:[0,0,1]
	s_nop 0
	v_cndmask_b32_e64 v34, 0, v72, s[10:11]
	v_cndmask_b32_e64 v35, 0, v73, s[10:11]
	v_cndmask_b32_e64 v42, 0, v72, s[20:21]
	v_cndmask_b32_e64 v43, 0, v73, s[20:21]
	v_cndmask_b32_e64 v32, 0, v74, s[10:11]
	v_cndmask_b32_e64 v33, 0, v75, s[10:11]
	v_cndmask_b32_e64 v40, 0, v74, s[20:21]
	v_cndmask_b32_e64 v41, 0, v75, s[20:21]
	v_cndmask_b32_e64 v38, 0, v76, s[10:11]
	v_cndmask_b32_e64 v39, 0, v77, s[10:11]
	v_cndmask_b32_e64 v46, 0, v76, s[20:21]
	v_cndmask_b32_e64 v47, 0, v77, s[20:21]
	v_cndmask_b32_e64 v36, 0, v78, s[10:11]
	v_cndmask_b32_e64 v37, 0, v79, s[10:11]
	v_cndmask_b32_e64 v44, 0, v78, s[20:21]
	v_cndmask_b32_e64 v45, 0, v79, s[20:21]
	s_or_b64 exec, exec, s[12:13]
	s_min_i32 s29, s30, 0x100
	s_ashr_i32 s16, s29, 4
	s_cmp_lt_i32 s16, 1
	s_mulk_i32 s0, 0x980
	s_cbranch_scc1 .LBB0_1458
; __device__ __forceinline__ void dsa_unit(int wv, const Args& A, LAS unsigned char* lds, int s, int qt) {
;     ...
;         DSA_LOADT(kf, 0);
;         for (int kt = 0; kt < nt; ++kt) {
;             long k1[8];
;             DSA_LOADT(k1, kt + 1);
	s_mul_i32 s12, s1, 0x980
	s_add_i32 s1, s1, s4
	v_lshl_add_u32 v141, v94, 1, s12
	v_add_u32_e32 v141, 0x13000, v141
	ds_read_u16 v107, v141
	ds_read_u16 v108, v141 offset:32
	ds_read_u16 v109, v141 offset:64
	ds_read_u16 v110, v141 offset:96
	ds_read_u16 v111, v141 offset:128
	ds_read_u16 v112, v141 offset:160
	ds_read_u16 v113, v141 offset:192
	ds_read_u16 v114, v141 offset:224
	ds_read_u16 v115, v141 offset:256
	ds_read_u16 v116, v141 offset:288
	ds_read_u16 v117, v141 offset:320
	ds_read_u16 v118, v141 offset:352
	ds_read_u16 v119, v141 offset:384
	ds_read_u16 v120, v141 offset:416
	ds_read_u16 v121, v141 offset:448
	ds_read_u16 v122, v141 offset:480
	v_mbcnt_lo_u32_b32 v144, -1, 0
	v_mbcnt_hi_u32_b32 v144, -1, v144
	v_lshl_add_u32 v30, v144, 3, s12
	v_add_u32_e32 v30, 0x13000, v30
	ds_read_b64 v[92:93], v30
	s_lshl_b32 s12, s12, 1
	v_lshl_add_u32 v28, v144, 4, s12
	v_add_u32_e32 v143, 0x1cc80, v103
	v_lshrrev_b32_e32 v144, 4, v144
	v_lshlrev_b32_e32 v144, 4, v144
	v_add_u32_e32 v29, s12, v144
	s_waitcnt lgkmcnt(0)
	v_add_lshl_u32 v107, s48, v107, 8
	v_add_u32_e32 v107, v144, v107
	global_load_dwordx4 v[56:59], v107, s[84:85]
	global_load_dwordx4 v[60:63], v107, s[84:85] offset:64
	global_load_dwordx4 v[64:67], v107, s[84:85] offset:128
	global_load_dwordx4 v[68:71], v107, s[84:85] offset:192
	s_cmp_gt_i32 s16, 1
	s_cbranch_scc0 .Lqk_ni_pre
	v_add_lshl_u32 v108, s48, v108, 8
	v_add_u32_e32 v108, v144, v108
	global_load_dwordx4 v[72:75], v108, s[84:85]
	global_load_dwordx4 v[76:79], v108, s[84:85] offset:64
	global_load_dwordx4 v[80:83], v108, s[84:85] offset:128
	global_load_dwordx4 v[84:87], v108, s[84:85] offset:192
	s_cmp_gt_i32 s16, 2
	s_cbranch_scc0 .Lqk_ni_pre
	v_add_lshl_u32 v109, s48, v109, 8
	v_add_u32_e32 v109, v144, v109
	global_load_dwordx4 v[124:127], v109, s[84:85]
	global_load_dwordx4 v[128:131], v109, s[84:85] offset:64
	global_load_dwordx4 v[132:135], v109, s[84:85] offset:128
	global_load_dwordx4 v[136:139], v109, s[84:85] offset:192
	s_cmp_gt_i32 s16, 3
	s_cbranch_scc0 .Lqk_ni_pre
	v_add_lshl_u32 v110, s48, v110, 8
	v_add_u32_e32 v110, v144, v110
	global_load_dwordx4 v[180:183], v110, s[84:85]
	global_load_dwordx4 v[184:187], v110, s[84:85] offset:64
	global_load_dwordx4 v[188:191], v110, s[84:85] offset:128
	global_load_dwordx4 v[192:195], v110, s[84:85] offset:192
	s_cmp_gt_i32 s16, 4
	s_cbranch_scc0 .Lqk_ni_pre
	v_add_lshl_u32 v111, s48, v111, 8
	v_add_u32_e32 v111, v144, v111
	global_load_dwordx4 v[196:199], v111, s[84:85]
	global_load_dwordx4 v[200:203], v111, s[84:85] offset:64
	global_load_dwordx4 v[204:207], v111, s[84:85] offset:128
	global_load_dwordx4 v[208:211], v111, s[84:85] offset:192
.Lqk_ni_pre:
	v_and_b32_e32 v145, 0xffff, v92
	v_lshrrev_b32_e32 v146, 16, v92
	v_and_b32_e32 v147, 0xffff, v93
	v_lshrrev_b32_e32 v148, 16, v93
	v_subrev_u32_e32 v145, s1, v145
	v_subrev_u32_e32 v146, s1, v146
	v_subrev_u32_e32 v147, s1, v147
	v_subrev_u32_e32 v148, s1, v148
	v_sub_u32_e32 v149, 0, v145
	v_sub_u32_e32 v158, 0, v146
	v_sub_u32_e32 v159, 0, v147
	v_sub_u32_e32 v160, 0, v148
	v_max_i32_e32 v149, v145, v149
	v_max_i32_e32 v158, v146, v158
	v_max_i32_e32 v159, v147, v159
	v_max_i32_e32 v160, v148, v160
	v_mul_u32_u24_e32 v161, v149, v149
	v_mul_u32_u24_e32 v162, v158, v158
	v_mul_u32_u24_e32 v163, v159, v159
	v_mul_u32_u24_e32 v164, v160, v160
	v_cvt_f32_u32_e32 v161, v161
	v_cvt_f32_u32_e32 v162, v162
	v_cvt_f32_u32_e32 v163, v163
	v_cvt_f32_u32_e32 v164, v164
	v_lshrrev_b32_e32 v161, 23, v161
	v_lshrrev_b32_e32 v162, 23, v162
	v_lshrrev_b32_e32 v163, 23, v163
	v_lshrrev_b32_e32 v164, 23, v164
	v_add_u32_e32 v161, 0xffffff83, v161
	v_add_u32_e32 v162, 0xffffff83, v162
	v_add_u32_e32 v163, 0xffffff83, v163
	v_add_u32_e32 v164, 0xffffff83, v164
	v_min_u32_e32 v161, 15, v161
	v_min_u32_e32 v162, 15, v162
	v_min_u32_e32 v163, 15, v163
	v_min_u32_e32 v164, 15, v164
	v_cmp_gt_u32_e32 vcc, 8, v149
	v_cmp_gt_u32_e64 s[26:27], 8, v158
	v_cmp_gt_u32_e64 s[36:37], 8, v159
	v_cmp_gt_u32_e64 s[38:39], 8, v160
	v_med3_i32 v165, v145, 0, 1
	v_med3_i32 v166, v146, 0, 1
	v_med3_i32 v167, v147, 0, 1
	v_med3_i32 v168, v148, 0, 1
	v_cndmask_b32_e64 v161, v161, v149, vcc
	v_cndmask_b32_e64 v162, v162, v158, s[26:27]
	v_cndmask_b32_e64 v163, v163, v159, s[36:37]
	v_cndmask_b32_e64 v164, v164, v160, s[38:39]
	v_lshl_add_u32 v161, v165, 4, v161
	v_lshl_add_u32 v162, v166, 4, v162
	v_lshl_add_u32 v163, v167, 4, v163
	v_lshl_add_u32 v164, v168, 4, v164
	v_lshlrev_b32_e32 v48, 5, v161
	v_lshlrev_b32_e32 v49, 5, v162
	v_lshlrev_b32_e32 v50, 5, v163
	v_lshlrev_b32_e32 v51, 5, v164
	ds_write_b128 v28, v[48:51]
	ds_read_b128 v[52:55], v29
	s_cmp_gt_i32 s16, 5
	s_cbranch_scc0 .Lqk_n5_0
	v_add_lshl_u32 v112, s48, v112, 8
	v_add_u32_e32 v112, v144, v112
	global_load_dwordx4 v[212:215], v112, s[84:85]
	global_load_dwordx4 v[216:219], v112, s[84:85] offset:64
	global_load_dwordx4 v[220:223], v112, s[84:85] offset:128
	global_load_dwordx4 v[224:227], v112, s[84:85] offset:192
	s_waitcnt vmcnt(20)
	s_branch .Lqk_go_0

; __device__ __forceinline__ void dsa_unit(int wv, const Args& A, LAS unsigned char* lds, int s, int qt) {
;     ...
;         for (int kt = 0; kt < nt; ++kt) {
;             long k1[8];
;             DSA_LOADT(k1, kt + 1);
;             f32x4 a = {0.f, 0.f, 0.f, 0.f};
; #pragma unroll
;             for (int kk = 0; kk < 8; ++kk) a = __builtin_amdgcn_mfma_f32_16x16x32_fp8_fp8(kf[kk], qf[kk], a, 0, 0, 0);
;             if (fr < 8) {
; #pragma unroll
;                 for (int r = 0; r < 4; ++r) { const int e2 = kt * 16 + fq * 4 + r; const int key2 = lst[e2];
;                     Pw[e2 * 8 + fr] = (h16)(a[r] * 0.0625f + relb[rel_bucket(key2 - qpos) * 8 + fr]); } }
; #pragma unroll
;             for (int kk = 0; kk < 8; ++kk) kf[kk] = k1[kk];
.Lqk_go_0:
	v_mfma_f32_16x16x32_fp8_fp8 v[88:91], v[56:57], v[34:35], 0
	v_mfma_f32_16x16x32_fp8_fp8 v[88:91], v[58:59], v[32:33], v[88:91]
	v_mfma_f32_16x16x32_fp8_fp8 v[88:91], v[60:61], v[38:39], v[88:91]
	v_mfma_f32_16x16x32_fp8_fp8 v[88:91], v[62:63], v[36:37], v[88:91]
	v_mfma_f32_16x16x32_fp8_fp8 v[88:91], v[64:65], v[42:43], v[88:91]
	v_mfma_f32_16x16x32_fp8_fp8 v[88:91], v[66:67], v[40:41], v[88:91]
	v_mfma_f32_16x16x32_fp8_fp8 v[88:91], v[68:69], v[46:47], v[88:91]
	v_mfma_f32_16x16x32_fp8_fp8 v[88:91], v[70:71], v[44:45], v[88:91]
	s_and_saveexec_b64 s[12:13], s[8:9]
	s_waitcnt lgkmcnt(0)
	v_add_u32_e32 v165, v52, v25
	v_add_u32_e32 v166, v53, v25
	v_add_u32_e32 v167, v54, v25
	v_add_u32_e32 v168, v55, v25
	ds_read_b32 v165, v165
	ds_read_b32 v166, v166
	ds_read_b32 v167, v167
	ds_read_b32 v168, v168
	s_waitcnt lgkmcnt(3)
	v_fma_mixlo_f16 v165, v88, s3, v165
	s_waitcnt lgkmcnt(2)
	v_fma_mixlo_f16 v166, v89, s3, v166
	s_waitcnt lgkmcnt(1)
	v_fma_mixlo_f16 v167, v90, s3, v167
	s_waitcnt lgkmcnt(0)
	v_fma_mixlo_f16 v168, v91, s3, v168
	ds_write_b16 v143, v165
	ds_write_b16 v143, v166 offset:16
	ds_write_b16 v143, v167 offset:32
	ds_write_b16 v143, v168 offset:48
	s_mov_b64 exec, s[12:13]
	s_cmp_le_i32 s16, 1
	s_cbranch_scc1 .Lqk_done
	ds_read_b128 v[52:55], v29 offset:64
	s_cmp_gt_i32 s16, 6
	s_cbranch_scc0 .Lqk_n5_1
	v_add_lshl_u32 v113, s48, v113, 8
	v_add_u32_e32 v113, v144, v113
	global_load_dwordx4 v[56:59], v113, s[84:85]
	global_load_dwordx4 v[60:63], v113, s[84:85] offset:64
	global_load_dwordx4 v[64:67], v113, s[84:85] offset:128
	global_load_dwordx4 v[68:71], v113, s[84:85] offset:192
	s_waitcnt vmcnt(20)
	s_branch .Lqk_go_1

; __device__ __forceinline__ void dsa_unit(int wv, const Args& A, LAS unsigned char* lds, int s, int qt) {
;     ...
;         for (int kt = 0; kt < nt; ++kt) {
;             long k1[8];
;             DSA_LOADT(k1, kt + 1);
;             f32x4 a = {0.f, 0.f, 0.f, 0.f};
; #pragma unroll
;             for (int kk = 0; kk < 8; ++kk) a = __builtin_amdgcn_mfma_f32_16x16x32_fp8_fp8(kf[kk], qf[kk], a, 0, 0, 0);
;             if (fr < 8) {
; #pragma unroll
;                 for (int r = 0; r < 4; ++r) { const int e2 = kt * 16 + fq * 4 + r; const int key2 = lst[e2];
;                     Pw[e2 * 8 + fr] = (h16)(a[r] * 0.0625f + relb[rel_bucket(key2 - qpos) * 8 + fr]); } }
; #pragma unroll
;             for (int kk = 0; kk < 8; ++kk) kf[kk] = k1[kk];
.Lqk_go_1:
	v_mfma_f32_16x16x32_fp8_fp8 v[88:91], v[72:73], v[34:35], 0
	v_mfma_f32_16x16x32_fp8_fp8 v[88:91], v[74:75], v[32:33], v[88:91]
	v_mfma_f32_16x16x32_fp8_fp8 v[88:91], v[76:77], v[38:39], v[88:91]
	v_mfma_f32_16x16x32_fp8_fp8 v[88:91], v[78:79], v[36:37], v[88:91]
	v_mfma_f32_16x16x32_fp8_fp8 v[88:91], v[80:81], v[42:43], v[88:91]
	v_mfma_f32_16x16x32_fp8_fp8 v[88:91], v[82:83], v[40:41], v[88:91]
	v_mfma_f32_16x16x32_fp8_fp8 v[88:91], v[84:85], v[46:47], v[88:91]
	v_mfma_f32_16x16x32_fp8_fp8 v[88:91], v[86:87], v[44:45], v[88:91]
	s_and_saveexec_b64 s[12:13], s[8:9]
	s_waitcnt lgkmcnt(0)
	v_add_u32_e32 v165, v52, v25
	v_add_u32_e32 v166, v53, v25
	v_add_u32_e32 v167, v54, v25
	v_add_u32_e32 v168, v55, v25
	ds_read_b32 v165, v165
	ds_read_b32 v166, v166
	ds_read_b32 v167, v167
	ds_read_b32 v168, v168
	s_waitcnt lgkmcnt(3)
	v_fma_mixlo_f16 v165, v88, s3, v165
	s_waitcnt lgkmcnt(2)
	v_fma_mixlo_f16 v166, v89, s3, v166
	s_waitcnt lgkmcnt(1)
	v_fma_mixlo_f16 v167, v90, s3, v167
	s_waitcnt lgkmcnt(0)
	v_fma_mixlo_f16 v168, v91, s3, v168
	ds_write_b16 v143, v165 offset:256
	ds_write_b16 v143, v166 offset:272
	ds_write_b16 v143, v167 offset:288
	ds_write_b16 v143, v168 offset:304
	s_mov_b64 exec, s[12:13]
	s_cmp_le_i32 s16, 2
	s_cbranch_scc1 .Lqk_done
	ds_read_b128 v[52:55], v29 offset:128
	s_cmp_gt_i32 s16, 7
	s_cbranch_scc0 .Lqk_n5_2
	v_add_lshl_u32 v114, s48, v114, 8
	v_add_u32_e32 v114, v144, v114
	global_load_dwordx4 v[72:75], v114, s[84:85]
	global_load_dwordx4 v[76:79], v114, s[84:85] offset:64
	global_load_dwordx4 v[80:83], v114, s[84:85] offset:128
	global_load_dwordx4 v[84:87], v114, s[84:85] offset:192
	s_waitcnt vmcnt(20)
	s_branch .Lqk_go_2

; __device__ __forceinline__ void dsa_unit(int wv, const Args& A, LAS unsigned char* lds, int s, int qt) {
;     ...
;         for (int kt = 0; kt < nt; ++kt) {
;             long k1[8];
;             DSA_LOADT(k1, kt + 1);
;             f32x4 a = {0.f, 0.f, 0.f, 0.f};
; #pragma unroll
;             for (int kk = 0; kk < 8; ++kk) a = __builtin_amdgcn_mfma_f32_16x16x32_fp8_fp8(kf[kk], qf[kk], a, 0, 0, 0);
;             if (fr < 8) {
; #pragma unroll
;                 for (int r = 0; r < 4; ++r) { const int e2 = kt * 16 + fq * 4 + r; const int key2 = lst[e2];
;                     Pw[e2 * 8 + fr] = (h16)(a[r] * 0.0625f + relb[rel_bucket(key2 - qpos) * 8 + fr]); } }
; #pragma unroll
;             for (int kk = 0; kk < 8; ++kk) kf[kk] = k1[kk];
.Lqk_go_2:
	v_mfma_f32_16x16x32_fp8_fp8 v[88:91], v[124:125], v[34:35], 0
	v_mfma_f32_16x16x32_fp8_fp8 v[88:91], v[126:127], v[32:33], v[88:91]
	v_mfma_f32_16x16x32_fp8_fp8 v[88:91], v[128:129], v[38:39], v[88:91]
	v_mfma_f32_16x16x32_fp8_fp8 v[88:91], v[130:131], v[36:37], v[88:91]
	v_mfma_f32_16x16x32_fp8_fp8 v[88:91], v[132:133], v[42:43], v[88:91]
	v_mfma_f32_16x16x32_fp8_fp8 v[88:91], v[134:135], v[40:41], v[88:91]
	v_mfma_f32_16x16x32_fp8_fp8 v[88:91], v[136:137], v[46:47], v[88:91]
	v_mfma_f32_16x16x32_fp8_fp8 v[88:91], v[138:139], v[44:45], v[88:91]
	s_and_saveexec_b64 s[12:13], s[8:9]
	s_waitcnt lgkmcnt(0)
	v_add_u32_e32 v165, v52, v25
	v_add_u32_e32 v166, v53, v25
	v_add_u32_e32 v167, v54, v25
	v_add_u32_e32 v168, v55, v25
	ds_read_b32 v165, v165
	ds_read_b32 v166, v166
	ds_read_b32 v167, v167
	ds_read_b32 v168, v168
	s_waitcnt lgkmcnt(3)
	v_fma_mixlo_f16 v165, v88, s3, v165
	s_waitcnt lgkmcnt(2)
	v_fma_mixlo_f16 v166, v89, s3, v166
	s_waitcnt lgkmcnt(1)
	v_fma_mixlo_f16 v167, v90, s3, v167
	s_waitcnt lgkmcnt(0)
	v_fma_mixlo_f16 v168, v91, s3, v168
	ds_write_b16 v143, v165 offset:512
	ds_write_b16 v143, v166 offset:528
	ds_write_b16 v143, v167 offset:544
	ds_write_b16 v143, v168 offset:560
	s_mov_b64 exec, s[12:13]
	s_cmp_le_i32 s16, 3
	s_cbranch_scc1 .Lqk_done
	ds_read_b128 v[52:55], v29 offset:192
	s_cmp_gt_i32 s16, 8
	s_cbranch_scc0 .Lqk_n5_3
	v_add_lshl_u32 v115, s48, v115, 8
	v_add_u32_e32 v115, v144, v115
	global_load_dwordx4 v[124:127], v115, s[84:85]
	global_load_dwordx4 v[128:131], v115, s[84:85] offset:64
	global_load_dwordx4 v[132:135], v115, s[84:85] offset:128
	global_load_dwordx4 v[136:139], v115, s[84:85] offset:192
	s_waitcnt vmcnt(20)
	s_branch .Lqk_go_3

; __device__ __forceinline__ void dsa_unit(int wv, const Args& A, LAS unsigned char* lds, int s, int qt) {
;     ...
;         for (int kt = 0; kt < nt; ++kt) {
;             long k1[8];
;             DSA_LOADT(k1, kt + 1);
;             f32x4 a = {0.f, 0.f, 0.f, 0.f};
; #pragma unroll
;             for (int kk = 0; kk < 8; ++kk) a = __builtin_amdgcn_mfma_f32_16x16x32_fp8_fp8(kf[kk], qf[kk], a, 0, 0, 0);
;             if (fr < 8) {
; #pragma unroll
;                 for (int r = 0; r < 4; ++r) { const int e2 = kt * 16 + fq * 4 + r; const int key2 = lst[e2];
;                     Pw[e2 * 8 + fr] = (h16)(a[r] * 0.0625f + relb[rel_bucket(key2 - qpos) * 8 + fr]); } }
; #pragma unroll
;             for (int kk = 0; kk < 8; ++kk) kf[kk] = k1[kk];
.Lqk_go_3:
	v_mfma_f32_16x16x32_fp8_fp8 v[88:91], v[180:181], v[34:35], 0
	v_mfma_f32_16x16x32_fp8_fp8 v[88:91], v[182:183], v[32:33], v[88:91]
	v_mfma_f32_16x16x32_fp8_fp8 v[88:91], v[184:185], v[38:39], v[88:91]
	v_mfma_f32_16x16x32_fp8_fp8 v[88:91], v[186:187], v[36:37], v[88:91]
	v_mfma_f32_16x16x32_fp8_fp8 v[88:91], v[188:189], v[42:43], v[88:91]
	v_mfma_f32_16x16x32_fp8_fp8 v[88:91], v[190:191], v[40:41], v[88:91]
	v_mfma_f32_16x16x32_fp8_fp8 v[88:91], v[192:193], v[46:47], v[88:91]
	v_mfma_f32_16x16x32_fp8_fp8 v[88:91], v[194:195], v[44:45], v[88:91]
	s_and_saveexec_b64 s[12:13], s[8:9]
	s_waitcnt lgkmcnt(0)
	v_add_u32_e32 v165, v52, v25
	v_add_u32_e32 v166, v53, v25
	v_add_u32_e32 v167, v54, v25
	v_add_u32_e32 v168, v55, v25
	ds_read_b32 v165, v165
	ds_read_b32 v166, v166
	ds_read_b32 v167, v167
	ds_read_b32 v168, v168
	s_waitcnt lgkmcnt(3)
	v_fma_mixlo_f16 v165, v88, s3, v165
	s_waitcnt lgkmcnt(2)
	v_fma_mixlo_f16 v166, v89, s3, v166
	s_waitcnt lgkmcnt(1)
	v_fma_mixlo_f16 v167, v90, s3, v167
	s_waitcnt lgkmcnt(0)
	v_fma_mixlo_f16 v168, v91, s3, v168
	ds_write_b16 v143, v165 offset:768
	ds_write_b16 v143, v166 offset:784
	ds_write_b16 v143, v167 offset:800
	ds_write_b16 v143, v168 offset:816
	s_mov_b64 exec, s[12:13]
	s_cmp_le_i32 s16, 4
	s_cbranch_scc1 .Lqk_done
	ds_read_b128 v[52:55], v29 offset:256
	s_cmp_gt_i32 s16, 9
	s_cbranch_scc0 .Lqk_n5_4
	v_add_lshl_u32 v116, s48, v116, 8
	v_add_u32_e32 v116, v144, v116
	global_load_dwordx4 v[180:183], v116, s[84:85]
	global_load_dwordx4 v[184:187], v116, s[84:85] offset:64
	global_load_dwordx4 v[188:191], v116, s[84:85] offset:128
	global_load_dwordx4 v[192:195], v116, s[84:85] offset:192
	s_waitcnt vmcnt(20)
	s_branch .Lqk_go_4

; __device__ __forceinline__ void dsa_unit(int wv, const Args& A, LAS unsigned char* lds, int s, int qt) {
;     ...
;         for (int kt = 0; kt < nt; ++kt) {
;             long k1[8];
;             DSA_LOADT(k1, kt + 1);
;             f32x4 a = {0.f, 0.f, 0.f, 0.f};
; #pragma unroll
;             for (int kk = 0; kk < 8; ++kk) a = __builtin_amdgcn_mfma_f32_16x16x32_fp8_fp8(kf[kk], qf[kk], a, 0, 0, 0);
;             if (fr < 8) {
; #pragma unroll
;                 for (int r = 0; r < 4; ++r) { const int e2 = kt * 16 + fq * 4 + r; const int key2 = lst[e2];
;                     Pw[e2 * 8 + fr] = (h16)(a[r] * 0.0625f + relb[rel_bucket(key2 - qpos) * 8 + fr]); } }
; #pragma unroll
;             for (int kk = 0; kk < 8; ++kk) kf[kk] = k1[kk];
.Lqk_go_4:
	v_mfma_f32_16x16x32_fp8_fp8 v[88:91], v[196:197], v[34:35], 0
	v_mfma_f32_16x16x32_fp8_fp8 v[88:91], v[198:199], v[32:33], v[88:91]
	v_mfma_f32_16x16x32_fp8_fp8 v[88:91], v[200:201], v[38:39], v[88:91]
	v_mfma_f32_16x16x32_fp8_fp8 v[88:91], v[202:203], v[36:37], v[88:91]
	v_mfma_f32_16x16x32_fp8_fp8 v[88:91], v[204:205], v[42:43], v[88:91]
	v_mfma_f32_16x16x32_fp8_fp8 v[88:91], v[206:207], v[40:41], v[88:91]
	v_mfma_f32_16x16x32_fp8_fp8 v[88:91], v[208:209], v[46:47], v[88:91]
	v_mfma_f32_16x16x32_fp8_fp8 v[88:91], v[210:211], v[44:45], v[88:91]
	s_and_saveexec_b64 s[12:13], s[8:9]
	s_waitcnt lgkmcnt(0)
	v_add_u32_e32 v165, v52, v25
	v_add_u32_e32 v166, v53, v25
	v_add_u32_e32 v167, v54, v25
	v_add_u32_e32 v168, v55, v25
	ds_read_b32 v165, v165
	ds_read_b32 v166, v166
	ds_read_b32 v167, v167
	ds_read_b32 v168, v168
	s_waitcnt lgkmcnt(3)
	v_fma_mixlo_f16 v165, v88, s3, v165
	s_waitcnt lgkmcnt(2)
	v_fma_mixlo_f16 v166, v89, s3, v166
	s_waitcnt lgkmcnt(1)
	v_fma_mixlo_f16 v167, v90, s3, v167
	s_waitcnt lgkmcnt(0)
	v_fma_mixlo_f16 v168, v91, s3, v168
	ds_write_b16 v143, v165 offset:1024
	ds_write_b16 v143, v166 offset:1040
	ds_write_b16 v143, v167 offset:1056
	ds_write_b16 v143, v168 offset:1072
	s_mov_b64 exec, s[12:13]
	s_cmp_le_i32 s16, 5
	s_cbranch_scc1 .Lqk_done
	ds_read_b128 v[52:55], v29 offset:320
	s_cmp_gt_i32 s16, 10
	s_cbranch_scc0 .Lqk_n5_5
	v_add_lshl_u32 v117, s48, v117, 8
	v_add_u32_e32 v117, v144, v117
	global_load_dwordx4 v[196:199], v117, s[84:85]
	global_load_dwordx4 v[200:203], v117, s[84:85] offset:64
	global_load_dwordx4 v[204:207], v117, s[84:85] offset:128
	global_load_dwordx4 v[208:211], v117, s[84:85] offset:192
	s_waitcnt vmcnt(20)
	s_branch .Lqk_go_5

; __device__ __forceinline__ void dsa_unit(int wv, const Args& A, LAS unsigned char* lds, int s, int qt) {
;     ...
;         for (int kt = 0; kt < nt; ++kt) {
;             long k1[8];
;             DSA_LOADT(k1, kt + 1);
;             f32x4 a = {0.f, 0.f, 0.f, 0.f};
; #pragma unroll
;             for (int kk = 0; kk < 8; ++kk) a = __builtin_amdgcn_mfma_f32_16x16x32_fp8_fp8(kf[kk], qf[kk], a, 0, 0, 0);
;             if (fr < 8) {
; #pragma unroll
;                 for (int r = 0; r < 4; ++r) { const int e2 = kt * 16 + fq * 4 + r; const int key2 = lst[e2];
;                     Pw[e2 * 8 + fr] = (h16)(a[r] * 0.0625f + relb[rel_bucket(key2 - qpos) * 8 + fr]); } }
; #pragma unroll
;             for (int kk = 0; kk < 8; ++kk) kf[kk] = k1[kk];
.Lqk_go_5:
	v_mfma_f32_16x16x32_fp8_fp8 v[88:91], v[212:213], v[34:35], 0
	v_mfma_f32_16x16x32_fp8_fp8 v[88:91], v[214:215], v[32:33], v[88:91]
	v_mfma_f32_16x16x32_fp8_fp8 v[88:91], v[216:217], v[38:39], v[88:91]
	v_mfma_f32_16x16x32_fp8_fp8 v[88:91], v[218:219], v[36:37], v[88:91]
	v_mfma_f32_16x16x32_fp8_fp8 v[88:91], v[220:221], v[42:43], v[88:91]
	v_mfma_f32_16x16x32_fp8_fp8 v[88:91], v[222:223], v[40:41], v[88:91]
	v_mfma_f32_16x16x32_fp8_fp8 v[88:91], v[224:225], v[46:47], v[88:91]
	v_mfma_f32_16x16x32_fp8_fp8 v[88:91], v[226:227], v[44:45], v[88:91]
	s_and_saveexec_b64 s[12:13], s[8:9]
	s_waitcnt lgkmcnt(0)
	v_add_u32_e32 v165, v52, v25
	v_add_u32_e32 v166, v53, v25
	v_add_u32_e32 v167, v54, v25
	v_add_u32_e32 v168, v55, v25
	ds_read_b32 v165, v165
	ds_read_b32 v166, v166
	ds_read_b32 v167, v167
	ds_read_b32 v168, v168
	s_waitcnt lgkmcnt(3)
	v_fma_mixlo_f16 v165, v88, s3, v165
	s_waitcnt lgkmcnt(2)
	v_fma_mixlo_f16 v166, v89, s3, v166
	s_waitcnt lgkmcnt(1)
	v_fma_mixlo_f16 v167, v90, s3, v167
	s_waitcnt lgkmcnt(0)
	v_fma_mixlo_f16 v168, v91, s3, v168
	ds_write_b16 v143, v165 offset:1280
	ds_write_b16 v143, v166 offset:1296
	ds_write_b16 v143, v167 offset:1312
	ds_write_b16 v143, v168 offset:1328
	s_mov_b64 exec, s[12:13]
	s_cmp_le_i32 s16, 6
	s_cbranch_scc1 .Lqk_done
	ds_read_b128 v[52:55], v29 offset:384
	s_cmp_gt_i32 s16, 11
	s_cbranch_scc0 .Lqk_n5_6
	v_add_lshl_u32 v118, s48, v118, 8
	v_add_u32_e32 v118, v144, v118
	global_load_dwordx4 v[212:215], v118, s[84:85]
	global_load_dwordx4 v[216:219], v118, s[84:85] offset:64
	global_load_dwordx4 v[220:223], v118, s[84:85] offset:128
	global_load_dwordx4 v[224:227], v118, s[84:85] offset:192
	s_waitcnt vmcnt(20)
	s_branch .Lqk_go_6

; __device__ __forceinline__ void dsa_unit(int wv, const Args& A, LAS unsigned char* lds, int s, int qt) {
;     ...
;         for (int kt = 0; kt < nt; ++kt) {
;             long k1[8];
;             DSA_LOADT(k1, kt + 1);
;             f32x4 a = {0.f, 0.f, 0.f, 0.f};
; #pragma unroll
;             for (int kk = 0; kk < 8; ++kk) a = __builtin_amdgcn_mfma_f32_16x16x32_fp8_fp8(kf[kk], qf[kk], a, 0, 0, 0);
;             if (fr < 8) {
; #pragma unroll
;                 for (int r = 0; r < 4; ++r) { const int e2 = kt * 16 + fq * 4 + r; const int key2 = lst[e2];
;                     Pw[e2 * 8 + fr] = (h16)(a[r] * 0.0625f + relb[rel_bucket(key2 - qpos) * 8 + fr]); } }
; #pragma unroll
;             for (int kk = 0; kk < 8; ++kk) kf[kk] = k1[kk];
.Lqk_go_6:
	v_mfma_f32_16x16x32_fp8_fp8 v[88:91], v[56:57], v[34:35], 0
	v_mfma_f32_16x16x32_fp8_fp8 v[88:91], v[58:59], v[32:33], v[88:91]
	v_mfma_f32_16x16x32_fp8_fp8 v[88:91], v[60:61], v[38:39], v[88:91]
	v_mfma_f32_16x16x32_fp8_fp8 v[88:91], v[62:63], v[36:37], v[88:91]
	v_mfma_f32_16x16x32_fp8_fp8 v[88:91], v[64:65], v[42:43], v[88:91]
	v_mfma_f32_16x16x32_fp8_fp8 v[88:91], v[66:67], v[40:41], v[88:91]
	v_mfma_f32_16x16x32_fp8_fp8 v[88:91], v[68:69], v[46:47], v[88:91]
	v_mfma_f32_16x16x32_fp8_fp8 v[88:91], v[70:71], v[44:45], v[88:91]
	s_and_saveexec_b64 s[12:13], s[8:9]
	s_waitcnt lgkmcnt(0)
	v_add_u32_e32 v165, v52, v25
	v_add_u32_e32 v166, v53, v25
	v_add_u32_e32 v167, v54, v25
	v_add_u32_e32 v168, v55, v25
	ds_read_b32 v165, v165
	ds_read_b32 v166, v166
	ds_read_b32 v167, v167
	ds_read_b32 v168, v168
	s_waitcnt lgkmcnt(3)
	v_fma_mixlo_f16 v165, v88, s3, v165
	s_waitcnt lgkmcnt(2)
	v_fma_mixlo_f16 v166, v89, s3, v166
	s_waitcnt lgkmcnt(1)
	v_fma_mixlo_f16 v167, v90, s3, v167
	s_waitcnt lgkmcnt(0)
	v_fma_mixlo_f16 v168, v91, s3, v168
	ds_write_b16 v143, v165 offset:1536
	ds_write_b16 v143, v166 offset:1552
	ds_write_b16 v143, v167 offset:1568
	ds_write_b16 v143, v168 offset:1584
	s_mov_b64 exec, s[12:13]
	s_cmp_le_i32 s16, 7
	s_cbranch_scc1 .Lqk_done
	ds_read_b128 v[52:55], v29 offset:448
	s_cmp_gt_i32 s16, 12
	s_cbranch_scc0 .Lqk_n5_7
	v_add_lshl_u32 v119, s48, v119, 8
	v_add_u32_e32 v119, v144, v119
	global_load_dwordx4 v[56:59], v119, s[84:85]
	global_load_dwordx4 v[60:63], v119, s[84:85] offset:64
	global_load_dwordx4 v[64:67], v119, s[84:85] offset:128
	global_load_dwordx4 v[68:71], v119, s[84:85] offset:192
	s_waitcnt vmcnt(20)
	s_branch .Lqk_go_7

; __device__ __forceinline__ void dsa_unit(int wv, const Args& A, LAS unsigned char* lds, int s, int qt) {
;     ...
;         for (int kt = 0; kt < nt; ++kt) {
;             long k1[8];
;             DSA_LOADT(k1, kt + 1);
;             f32x4 a = {0.f, 0.f, 0.f, 0.f};
; #pragma unroll
;             for (int kk = 0; kk < 8; ++kk) a = __builtin_amdgcn_mfma_f32_16x16x32_fp8_fp8(kf[kk], qf[kk], a, 0, 0, 0);
;             if (fr < 8) {
; #pragma unroll
;                 for (int r = 0; r < 4; ++r) { const int e2 = kt * 16 + fq * 4 + r; const int key2 = lst[e2];
;                     Pw[e2 * 8 + fr] = (h16)(a[r] * 0.0625f + relb[rel_bucket(key2 - qpos) * 8 + fr]); } }
; #pragma unroll
;             for (int kk = 0; kk < 8; ++kk) kf[kk] = k1[kk];
.Lqk_go_7:
	v_mfma_f32_16x16x32_fp8_fp8 v[88:91], v[72:73], v[34:35], 0
	v_mfma_f32_16x16x32_fp8_fp8 v[88:91], v[74:75], v[32:33], v[88:91]
	v_mfma_f32_16x16x32_fp8_fp8 v[88:91], v[76:77], v[38:39], v[88:91]
	v_mfma_f32_16x16x32_fp8_fp8 v[88:91], v[78:79], v[36:37], v[88:91]
	v_mfma_f32_16x16x32_fp8_fp8 v[88:91], v[80:81], v[42:43], v[88:91]
	v_mfma_f32_16x16x32_fp8_fp8 v[88:91], v[82:83], v[40:41], v[88:91]
	v_mfma_f32_16x16x32_fp8_fp8 v[88:91], v[84:85], v[46:47], v[88:91]
	v_mfma_f32_16x16x32_fp8_fp8 v[88:91], v[86:87], v[44:45], v[88:91]
	s_and_saveexec_b64 s[12:13], s[8:9]
	s_waitcnt lgkmcnt(0)
	v_add_u32_e32 v165, v52, v25
	v_add_u32_e32 v166, v53, v25
	v_add_u32_e32 v167, v54, v25
	v_add_u32_e32 v168, v55, v25
	ds_read_b32 v165, v165
	ds_read_b32 v166, v166
	ds_read_b32 v167, v167
	ds_read_b32 v168, v168
	s_waitcnt lgkmcnt(3)
	v_fma_mixlo_f16 v165, v88, s3, v165
	s_waitcnt lgkmcnt(2)
	v_fma_mixlo_f16 v166, v89, s3, v166
	s_waitcnt lgkmcnt(1)
	v_fma_mixlo_f16 v167, v90, s3, v167
	s_waitcnt lgkmcnt(0)
	v_fma_mixlo_f16 v168, v91, s3, v168
	ds_write_b16 v143, v165 offset:1792
	ds_write_b16 v143, v166 offset:1808
	ds_write_b16 v143, v167 offset:1824
	ds_write_b16 v143, v168 offset:1840
	s_mov_b64 exec, s[12:13]
	s_cmp_le_i32 s16, 8
	s_cbranch_scc1 .Lqk_done
	ds_read_b128 v[52:55], v29 offset:512
	s_cmp_gt_i32 s16, 13
	s_cbranch_scc0 .Lqk_n5_8
	v_add_lshl_u32 v120, s48, v120, 8
	v_add_u32_e32 v120, v144, v120
	global_load_dwordx4 v[72:75], v120, s[84:85]
	global_load_dwordx4 v[76:79], v120, s[84:85] offset:64
	global_load_dwordx4 v[80:83], v120, s[84:85] offset:128
	global_load_dwordx4 v[84:87], v120, s[84:85] offset:192
	s_waitcnt vmcnt(20)
	s_branch .Lqk_go_8

; __device__ __forceinline__ void dsa_unit(int wv, const Args& A, LAS unsigned char* lds, int s, int qt) {
;     ...
;         for (int kt = 0; kt < nt; ++kt) {
;             long k1[8];
;             DSA_LOADT(k1, kt + 1);
;             f32x4 a = {0.f, 0.f, 0.f, 0.f};
; #pragma unroll
;             for (int kk = 0; kk < 8; ++kk) a = __builtin_amdgcn_mfma_f32_16x16x32_fp8_fp8(kf[kk], qf[kk], a, 0, 0, 0);
;             if (fr < 8) {
; #pragma unroll
;                 for (int r = 0; r < 4; ++r) { const int e2 = kt * 16 + fq * 4 + r; const int key2 = lst[e2];
;                     Pw[e2 * 8 + fr] = (h16)(a[r] * 0.0625f + relb[rel_bucket(key2 - qpos) * 8 + fr]); } }
; #pragma unroll
;             for (int kk = 0; kk < 8; ++kk) kf[kk] = k1[kk];
.Lqk_go_8:
	v_mfma_f32_16x16x32_fp8_fp8 v[88:91], v[124:125], v[34:35], 0
	v_mfma_f32_16x16x32_fp8_fp8 v[88:91], v[126:127], v[32:33], v[88:91]
	v_mfma_f32_16x16x32_fp8_fp8 v[88:91], v[128:129], v[38:39], v[88:91]
	v_mfma_f32_16x16x32_fp8_fp8 v[88:91], v[130:131], v[36:37], v[88:91]
	v_mfma_f32_16x16x32_fp8_fp8 v[88:91], v[132:133], v[42:43], v[88:91]
	v_mfma_f32_16x16x32_fp8_fp8 v[88:91], v[134:135], v[40:41], v[88:91]
	v_mfma_f32_16x16x32_fp8_fp8 v[88:91], v[136:137], v[46:47], v[88:91]
	v_mfma_f32_16x16x32_fp8_fp8 v[88:91], v[138:139], v[44:45], v[88:91]
	s_and_saveexec_b64 s[12:13], s[8:9]
	s_waitcnt lgkmcnt(0)
	v_add_u32_e32 v165, v52, v25
	v_add_u32_e32 v166, v53, v25
	v_add_u32_e32 v167, v54, v25
	v_add_u32_e32 v168, v55, v25
	ds_read_b32 v165, v165
	ds_read_b32 v166, v166
	ds_read_b32 v167, v167
	ds_read_b32 v168, v168
	s_waitcnt lgkmcnt(3)
	v_fma_mixlo_f16 v165, v88, s3, v165
	s_waitcnt lgkmcnt(2)
	v_fma_mixlo_f16 v166, v89, s3, v166
	s_waitcnt lgkmcnt(1)
	v_fma_mixlo_f16 v167, v90, s3, v167
	s_waitcnt lgkmcnt(0)
	v_fma_mixlo_f16 v168, v91, s3, v168
	ds_write_b16 v143, v165 offset:2048
	ds_write_b16 v143, v166 offset:2064
	ds_write_b16 v143, v167 offset:2080
	ds_write_b16 v143, v168 offset:2096
	s_mov_b64 exec, s[12:13]
	s_cmp_le_i32 s16, 9
	s_cbranch_scc1 .Lqk_done
	ds_read_b128 v[52:55], v29 offset:576
	s_cmp_gt_i32 s16, 14
	s_cbranch_scc0 .Lqk_n5_9
	v_add_lshl_u32 v121, s48, v121, 8
	v_add_u32_e32 v121, v144, v121
	global_load_dwordx4 v[124:127], v121, s[84:85]
	global_load_dwordx4 v[128:131], v121, s[84:85] offset:64
	global_load_dwordx4 v[132:135], v121, s[84:85] offset:128
	global_load_dwordx4 v[136:139], v121, s[84:85] offset:192
	s_waitcnt vmcnt(20)
	s_branch .Lqk_go_9

; __device__ __forceinline__ void dsa_unit(int wv, const Args& A, LAS unsigned char* lds, int s, int qt) {
;     ...
;         for (int kt = 0; kt < nt; ++kt) {
;             long k1[8];
;             DSA_LOADT(k1, kt + 1);
;             f32x4 a = {0.f, 0.f, 0.f, 0.f};
; #pragma unroll
;             for (int kk = 0; kk < 8; ++kk) a = __builtin_amdgcn_mfma_f32_16x16x32_fp8_fp8(kf[kk], qf[kk], a, 0, 0, 0);
;             if (fr < 8) {
; #pragma unroll
;                 for (int r = 0; r < 4; ++r) { const int e2 = kt * 16 + fq * 4 + r; const int key2 = lst[e2];
;                     Pw[e2 * 8 + fr] = (h16)(a[r] * 0.0625f + relb[rel_bucket(key2 - qpos) * 8 + fr]); } }
; #pragma unroll
;             for (int kk = 0; kk < 8; ++kk) kf[kk] = k1[kk];
.Lqk_go_9:
	v_mfma_f32_16x16x32_fp8_fp8 v[88:91], v[180:181], v[34:35], 0
	v_mfma_f32_16x16x32_fp8_fp8 v[88:91], v[182:183], v[32:33], v[88:91]
	v_mfma_f32_16x16x32_fp8_fp8 v[88:91], v[184:185], v[38:39], v[88:91]
	v_mfma_f32_16x16x32_fp8_fp8 v[88:91], v[186:187], v[36:37], v[88:91]
	v_mfma_f32_16x16x32_fp8_fp8 v[88:91], v[188:189], v[42:43], v[88:91]
	v_mfma_f32_16x16x32_fp8_fp8 v[88:91], v[190:191], v[40:41], v[88:91]
	v_mfma_f32_16x16x32_fp8_fp8 v[88:91], v[192:193], v[46:47], v[88:91]
	v_mfma_f32_16x16x32_fp8_fp8 v[88:91], v[194:195], v[44:45], v[88:91]
	s_and_saveexec_b64 s[12:13], s[8:9]
	s_waitcnt lgkmcnt(0)
	v_add_u32_e32 v165, v52, v25
	v_add_u32_e32 v166, v53, v25
	v_add_u32_e32 v167, v54, v25
	v_add_u32_e32 v168, v55, v25
	ds_read_b32 v165, v165
	ds_read_b32 v166, v166
	ds_read_b32 v167, v167
	ds_read_b32 v168, v168
	s_waitcnt lgkmcnt(3)
	v_fma_mixlo_f16 v165, v88, s3, v165
	s_waitcnt lgkmcnt(2)
	v_fma_mixlo_f16 v166, v89, s3, v166
	s_waitcnt lgkmcnt(1)
	v_fma_mixlo_f16 v167, v90, s3, v167
	s_waitcnt lgkmcnt(0)
	v_fma_mixlo_f16 v168, v91, s3, v168
	ds_write_b16 v143, v165 offset:2304
	ds_write_b16 v143, v166 offset:2320
	ds_write_b16 v143, v167 offset:2336
	ds_write_b16 v143, v168 offset:2352
	s_mov_b64 exec, s[12:13]
	s_cmp_le_i32 s16, 10
	s_cbranch_scc1 .Lqk_done
	ds_read_b128 v[52:55], v29 offset:640
	s_cmp_gt_i32 s16, 15
	s_cbranch_scc0 .Lqk_n5_10
	v_add_lshl_u32 v122, s48, v122, 8
	v_add_u32_e32 v122, v144, v122
	global_load_dwordx4 v[180:183], v122, s[84:85]
	global_load_dwordx4 v[184:187], v122, s[84:85] offset:64
	global_load_dwordx4 v[188:191], v122, s[84:85] offset:128
	global_load_dwordx4 v[192:195], v122, s[84:85] offset:192
	s_waitcnt vmcnt(20)
	s_branch .Lqk_go_10

; __device__ __forceinline__ void dsa_unit(int wv, const Args& A, LAS unsigned char* lds, int s, int qt) {
;     ...
;         for (int kt = 0; kt < nt; ++kt) {
;             long k1[8];
;             DSA_LOADT(k1, kt + 1);
;             f32x4 a = {0.f, 0.f, 0.f, 0.f};
; #pragma unroll
;             for (int kk = 0; kk < 8; ++kk) a = __builtin_amdgcn_mfma_f32_16x16x32_fp8_fp8(kf[kk], qf[kk], a, 0, 0, 0);
;             if (fr < 8) {
; #pragma unroll
;                 for (int r = 0; r < 4; ++r) { const int e2 = kt * 16 + fq * 4 + r; const int key2 = lst[e2];
;                     Pw[e2 * 8 + fr] = (h16)(a[r] * 0.0625f + relb[rel_bucket(key2 - qpos) * 8 + fr]); } }
; #pragma unroll
;             for (int kk = 0; kk < 8; ++kk) kf[kk] = k1[kk];
.Lqk_go_10:
	v_mfma_f32_16x16x32_fp8_fp8 v[88:91], v[196:197], v[34:35], 0
	v_mfma_f32_16x16x32_fp8_fp8 v[88:91], v[198:199], v[32:33], v[88:91]
	v_mfma_f32_16x16x32_fp8_fp8 v[88:91], v[200:201], v[38:39], v[88:91]
	v_mfma_f32_16x16x32_fp8_fp8 v[88:91], v[202:203], v[36:37], v[88:91]
	v_mfma_f32_16x16x32_fp8_fp8 v[88:91], v[204:205], v[42:43], v[88:91]
	v_mfma_f32_16x16x32_fp8_fp8 v[88:91], v[206:207], v[40:41], v[88:91]
	v_mfma_f32_16x16x32_fp8_fp8 v[88:91], v[208:209], v[46:47], v[88:91]
	v_mfma_f32_16x16x32_fp8_fp8 v[88:91], v[210:211], v[44:45], v[88:91]
	s_and_saveexec_b64 s[12:13], s[8:9]
	s_waitcnt lgkmcnt(0)
	v_add_u32_e32 v165, v52, v25
	v_add_u32_e32 v166, v53, v25
	v_add_u32_e32 v167, v54, v25
	v_add_u32_e32 v168, v55, v25
	ds_read_b32 v165, v165
	ds_read_b32 v166, v166
	ds_read_b32 v167, v167
	ds_read_b32 v168, v168
	s_waitcnt lgkmcnt(3)
	v_fma_mixlo_f16 v165, v88, s3, v165
	s_waitcnt lgkmcnt(2)
	v_fma_mixlo_f16 v166, v89, s3, v166
	s_waitcnt lgkmcnt(1)
	v_fma_mixlo_f16 v167, v90, s3, v167
	s_waitcnt lgkmcnt(0)
	v_fma_mixlo_f16 v168, v91, s3, v168
	ds_write_b16 v143, v165 offset:2560
	ds_write_b16 v143, v166 offset:2576
	ds_write_b16 v143, v167 offset:2592
	ds_write_b16 v143, v168 offset:2608
	s_mov_b64 exec, s[12:13]
	s_cmp_le_i32 s16, 11
	s_cbranch_scc1 .Lqk_done
	ds_read_b128 v[52:55], v29 offset:704
	s_cmp_gt_i32 s16, 15
	s_cbranch_scc0 .Lqk_n4_11
	s_waitcnt vmcnt(16)
	s_branch .Lqk_go_11

; __device__ __forceinline__ void dsa_unit(int wv, const Args& A, LAS unsigned char* lds, int s, int qt) {
;     ...
;         for (int kt = 0; kt < nt; ++kt) {
;             long k1[8];
;             DSA_LOADT(k1, kt + 1);
;             f32x4 a = {0.f, 0.f, 0.f, 0.f};
; #pragma unroll
;             for (int kk = 0; kk < 8; ++kk) a = __builtin_amdgcn_mfma_f32_16x16x32_fp8_fp8(kf[kk], qf[kk], a, 0, 0, 0);
;             if (fr < 8) {
; #pragma unroll
;                 for (int r = 0; r < 4; ++r) { const int e2 = kt * 16 + fq * 4 + r; const int key2 = lst[e2];
;                     Pw[e2 * 8 + fr] = (h16)(a[r] * 0.0625f + relb[rel_bucket(key2 - qpos) * 8 + fr]); } }
; #pragma unroll
;             for (int kk = 0; kk < 8; ++kk) kf[kk] = k1[kk];
.Lqk_go_11:
	v_mfma_f32_16x16x32_fp8_fp8 v[88:91], v[212:213], v[34:35], 0
	v_mfma_f32_16x16x32_fp8_fp8 v[88:91], v[214:215], v[32:33], v[88:91]
	v_mfma_f32_16x16x32_fp8_fp8 v[88:91], v[216:217], v[38:39], v[88:91]
	v_mfma_f32_16x16x32_fp8_fp8 v[88:91], v[218:219], v[36:37], v[88:91]
	v_mfma_f32_16x16x32_fp8_fp8 v[88:91], v[220:221], v[42:43], v[88:91]
	v_mfma_f32_16x16x32_fp8_fp8 v[88:91], v[222:223], v[40:41], v[88:91]
	v_mfma_f32_16x16x32_fp8_fp8 v[88:91], v[224:225], v[46:47], v[88:91]
	v_mfma_f32_16x16x32_fp8_fp8 v[88:91], v[226:227], v[44:45], v[88:91]
	s_and_saveexec_b64 s[12:13], s[8:9]
	s_waitcnt lgkmcnt(0)
	v_add_u32_e32 v165, v52, v25
	v_add_u32_e32 v166, v53, v25
	v_add_u32_e32 v167, v54, v25
	v_add_u32_e32 v168, v55, v25
	ds_read_b32 v165, v165
	ds_read_b32 v166, v166
	ds_read_b32 v167, v167
	ds_read_b32 v168, v168
	s_waitcnt lgkmcnt(3)
	v_fma_mixlo_f16 v165, v88, s3, v165
	s_waitcnt lgkmcnt(2)
	v_fma_mixlo_f16 v166, v89, s3, v166
	s_waitcnt lgkmcnt(1)
	v_fma_mixlo_f16 v167, v90, s3, v167
	s_waitcnt lgkmcnt(0)
	v_fma_mixlo_f16 v168, v91, s3, v168
	ds_write_b16 v143, v165 offset:2816
	ds_write_b16 v143, v166 offset:2832
	ds_write_b16 v143, v167 offset:2848
	ds_write_b16 v143, v168 offset:2864
	s_mov_b64 exec, s[12:13]
	s_cmp_le_i32 s16, 12
	s_cbranch_scc1 .Lqk_done
	ds_read_b128 v[52:55], v29 offset:768
	s_cmp_gt_i32 s16, 15
	s_cbranch_scc0 .Lqk_n3_12
	s_waitcnt vmcnt(12)
	s_branch .Lqk_go_12

; __device__ __forceinline__ void dsa_unit(int wv, const Args& A, LAS unsigned char* lds, int s, int qt) {
;     ...
;         for (int kt = 0; kt < nt; ++kt) {
;             long k1[8];
;             DSA_LOADT(k1, kt + 1);
;             f32x4 a = {0.f, 0.f, 0.f, 0.f};
; #pragma unroll
;             for (int kk = 0; kk < 8; ++kk) a = __builtin_amdgcn_mfma_f32_16x16x32_fp8_fp8(kf[kk], qf[kk], a, 0, 0, 0);
;             if (fr < 8) {
; #pragma unroll
;                 for (int r = 0; r < 4; ++r) { const int e2 = kt * 16 + fq * 4 + r; const int key2 = lst[e2];
;                     Pw[e2 * 8 + fr] = (h16)(a[r] * 0.0625f + relb[rel_bucket(key2 - qpos) * 8 + fr]); } }
; #pragma unroll
;             for (int kk = 0; kk < 8; ++kk) kf[kk] = k1[kk];
.Lqk_go_12:
	v_mfma_f32_16x16x32_fp8_fp8 v[88:91], v[56:57], v[34:35], 0
	v_mfma_f32_16x16x32_fp8_fp8 v[88:91], v[58:59], v[32:33], v[88:91]
	v_mfma_f32_16x16x32_fp8_fp8 v[88:91], v[60:61], v[38:39], v[88:91]
	v_mfma_f32_16x16x32_fp8_fp8 v[88:91], v[62:63], v[36:37], v[88:91]
	v_mfma_f32_16x16x32_fp8_fp8 v[88:91], v[64:65], v[42:43], v[88:91]
	v_mfma_f32_16x16x32_fp8_fp8 v[88:91], v[66:67], v[40:41], v[88:91]
	v_mfma_f32_16x16x32_fp8_fp8 v[88:91], v[68:69], v[46:47], v[88:91]
	v_mfma_f32_16x16x32_fp8_fp8 v[88:91], v[70:71], v[44:45], v[88:91]
	s_and_saveexec_b64 s[12:13], s[8:9]
	s_waitcnt lgkmcnt(0)
	v_add_u32_e32 v165, v52, v25
	v_add_u32_e32 v166, v53, v25
	v_add_u32_e32 v167, v54, v25
	v_add_u32_e32 v168, v55, v25
	ds_read_b32 v165, v165
	ds_read_b32 v166, v166
	ds_read_b32 v167, v167
	ds_read_b32 v168, v168
	s_waitcnt lgkmcnt(3)
	v_fma_mixlo_f16 v165, v88, s3, v165
	s_waitcnt lgkmcnt(2)
	v_fma_mixlo_f16 v166, v89, s3, v166
	s_waitcnt lgkmcnt(1)
	v_fma_mixlo_f16 v167, v90, s3, v167
	s_waitcnt lgkmcnt(0)
	v_fma_mixlo_f16 v168, v91, s3, v168
	ds_write_b16 v143, v165 offset:3072
	ds_write_b16 v143, v166 offset:3088
	ds_write_b16 v143, v167 offset:3104
	ds_write_b16 v143, v168 offset:3120
	s_mov_b64 exec, s[12:13]
	s_cmp_le_i32 s16, 13
	s_cbranch_scc1 .Lqk_done
	ds_read_b128 v[52:55], v29 offset:832
	s_cmp_gt_i32 s16, 15
	s_cbranch_scc0 .Lqk_n2_13
	s_waitcnt vmcnt(8)
	s_branch .Lqk_go_13

; __device__ __forceinline__ void dsa_unit(int wv, const Args& A, LAS unsigned char* lds, int s, int qt) {
;     ...
;         for (int kt = 0; kt < nt; ++kt) {
;             long k1[8];
;             DSA_LOADT(k1, kt + 1);
;             f32x4 a = {0.f, 0.f, 0.f, 0.f};
; #pragma unroll
;             for (int kk = 0; kk < 8; ++kk) a = __builtin_amdgcn_mfma_f32_16x16x32_fp8_fp8(kf[kk], qf[kk], a, 0, 0, 0);
;             if (fr < 8) {
; #pragma unroll
;                 for (int r = 0; r < 4; ++r) { const int e2 = kt * 16 + fq * 4 + r; const int key2 = lst[e2];
;                     Pw[e2 * 8 + fr] = (h16)(a[r] * 0.0625f + relb[rel_bucket(key2 - qpos) * 8 + fr]); } }
; #pragma unroll
;             for (int kk = 0; kk < 8; ++kk) kf[kk] = k1[kk];
.Lqk_go_15:
	v_mfma_f32_16x16x32_fp8_fp8 v[88:91], v[180:181], v[34:35], 0
	v_mfma_f32_16x16x32_fp8_fp8 v[88:91], v[182:183], v[32:33], v[88:91]
	v_mfma_f32_16x16x32_fp8_fp8 v[88:91], v[184:185], v[38:39], v[88:91]
	v_mfma_f32_16x16x32_fp8_fp8 v[88:91], v[186:187], v[36:37], v[88:91]
	v_mfma_f32_16x16x32_fp8_fp8 v[88:91], v[188:189], v[42:43], v[88:91]
	v_mfma_f32_16x16x32_fp8_fp8 v[88:91], v[190:191], v[40:41], v[88:91]
	v_mfma_f32_16x16x32_fp8_fp8 v[88:91], v[192:193], v[46:47], v[88:91]
	v_mfma_f32_16x16x32_fp8_fp8 v[88:91], v[194:195], v[44:45], v[88:91]
	s_and_saveexec_b64 s[12:13], s[8:9]
	s_waitcnt lgkmcnt(0)
	v_add_u32_e32 v165, v52, v25
	v_add_u32_e32 v166, v53, v25
	v_add_u32_e32 v167, v54, v25
	v_add_u32_e32 v168, v55, v25
	ds_read_b32 v165, v165
	ds_read_b32 v166, v166
	ds_read_b32 v167, v167
	ds_read_b32 v168, v168
	s_waitcnt lgkmcnt(3)
	v_fma_mixlo_f16 v165, v88, s3, v165
	s_waitcnt lgkmcnt(2)
	v_fma_mixlo_f16 v166, v89, s3, v166
	s_waitcnt lgkmcnt(1)
	v_fma_mixlo_f16 v167, v90, s3, v167
	s_waitcnt lgkmcnt(0)
	v_fma_mixlo_f16 v168, v91, s3, v168
	ds_write_b16 v143, v165 offset:3840
	ds_write_b16 v143, v166 offset:3856
	ds_write_b16 v143, v167 offset:3872
	ds_write_b16 v143, v168 offset:3888
	s_mov_b64 exec, s[12:13]
